# up-projection epilogue: dropped the canonicalizing v_max in front of each relu max (store-data WAR distances re-padded)
# speedup vs baseline: 1.0016x; 1.0016x over previous
.LBB0_646:
	s_and_b64 vcc, exec, s[56:57]
	s_cbranch_vccz .LBB0_648
	s_lshl_b32 s0, s40, 8
	s_add_i32 s0, s0, s25
	v_or_b32_e32 v136, s0, v154
	s_lshl_b32 s0, s34, 8
	s_or_b32 s0, s0, s43
	v_max_f32_e32 v132, 0, v12
	s_waitcnt lgkmcnt(0)
	v_lshl_add_u32 v18, v165, 3, s0
	v_mul_f32_e32 v134, v132, v132
	v_max_f32_e32 v133, 0, v13
	v_ashrrev_i32_e32 v19, 31, v18
	v_ashrrev_i32_e32 v137, 31, v136
	v_max_f32_e32 v132, 0, v9
	v_mul_f32_e32 v135, v133, v133
	v_lshl_add_u64 v[138:139], v[18:19], 1, s[52:53]
	v_lshlrev_b64 v[18:19], 13, v[136:137]
	v_max_f32_e32 v17, 0, v8
	v_mul_f32_e32 v132, v132, v132
	v_max_f32_e32 v133, 0, v10
	v_lshl_add_u64 v[18:19], v[138:139], 0, v[18:19]
	v_mul_f32_e32 v17, v17, v17
	v_max_f32_e32 v137, 0, v14
	v_mul_f32_e32 v133, v133, v133
	v_max_f32_e32 v140, 0, v11
	v_max_f32_e32 v141, 0, v15
	v_cvt_pk_bf16_f32 v132, v17, v132
	v_mul_f32_e32 v137, v137, v137
	v_mul_f32_e32 v140, v140, v140
	v_mul_f32_e32 v141, v141, v141
	v_cvt_pk_bf16_f32 v133, v133, v140
	v_cvt_pk_bf16_f32 v134, v134, v135
	v_cvt_pk_bf16_f32 v135, v137, v141
	global_store_dwordx4 v[18:19], v[132:135], off
	s_nop 1
	v_max_f32_e32 v17, 0, v0
	v_max_f32_e32 v132, 0, v4
	v_mul_f32_e32 v134, v132, v132
	v_max_f32_e32 v133, 0, v5
	v_max_f32_e32 v132, 0, v1
	v_mul_f32_e32 v135, v133, v133
	v_mul_f32_e32 v132, v132, v132
	v_max_f32_e32 v133, 0, v2
	v_mul_f32_e32 v17, v17, v17
	v_max_f32_e32 v137, 0, v6
	v_mul_f32_e32 v133, v133, v133
	v_max_f32_e32 v140, 0, v3
	v_max_f32_e32 v141, 0, v7
	v_cvt_pk_bf16_f32 v132, v17, v132
	v_mul_f32_e32 v137, v137, v137
	v_mul_f32_e32 v140, v140, v140
	v_mul_f32_e32 v141, v141, v141
	v_cvt_pk_bf16_f32 v133, v133, v140
	v_cvt_pk_bf16_f32 v134, v134, v135
	v_cvt_pk_bf16_f32 v135, v137, v141
	global_store_dwordx4 v[18:19], v[132:135], off offset:256
	s_nop 1
	v_max_f32_e32 v17, 0, v28
	v_or_b32_e32 v132, 16, v136
	v_ashrrev_i32_e32 v133, 31, v132
	v_lshlrev_b64 v[132:133], 13, v[132:133]
	v_lshl_add_u64 v[140:141], v[138:139], 0, v[132:133]
	v_max_f32_e32 v132, 0, v32
	v_mul_f32_e32 v134, v132, v132
	v_max_f32_e32 v133, 0, v33
	v_max_f32_e32 v132, 0, v29
	v_mul_f32_e32 v135, v133, v133
	v_mul_f32_e32 v132, v132, v132
	v_max_f32_e32 v133, 0, v30
	v_mul_f32_e32 v17, v17, v17
	v_max_f32_e32 v137, 0, v34
	v_mul_f32_e32 v133, v133, v133
	v_max_f32_e32 v142, 0, v31
	v_max_f32_e32 v143, 0, v35
	v_cvt_pk_bf16_f32 v132, v17, v132
	v_mul_f32_e32 v137, v137, v137
	v_mul_f32_e32 v142, v142, v142
	v_mul_f32_e32 v143, v143, v143
	v_cvt_pk_bf16_f32 v133, v133, v142
	v_cvt_pk_bf16_f32 v134, v134, v135
	v_cvt_pk_bf16_f32 v135, v137, v143
	global_store_dwordx4 v[140:141], v[132:135], off
	s_nop 1
	v_max_f32_e32 v17, 0, v20
	v_max_f32_e32 v132, 0, v24
	v_mul_f32_e32 v134, v132, v132
	v_max_f32_e32 v133, 0, v25
	v_max_f32_e32 v132, 0, v21
	v_mul_f32_e32 v135, v133, v133
	v_mul_f32_e32 v132, v132, v132
	v_max_f32_e32 v133, 0, v22
	v_mul_f32_e32 v17, v17, v17
	v_max_f32_e32 v137, 0, v26
	v_mul_f32_e32 v133, v133, v133
	v_max_f32_e32 v142, 0, v23
	v_max_f32_e32 v143, 0, v27
	v_cvt_pk_bf16_f32 v132, v17, v132
	v_mul_f32_e32 v137, v137, v137
	v_mul_f32_e32 v142, v142, v142
	v_mul_f32_e32 v143, v143, v143
	v_cvt_pk_bf16_f32 v133, v133, v142
	v_cvt_pk_bf16_f32 v134, v134, v135
	v_cvt_pk_bf16_f32 v135, v137, v143
	global_store_dwordx4 v[140:141], v[132:135], off offset:256
	s_nop 1
	v_max_f32_e32 v17, 0, v36
	v_or_b32_e32 v132, 32, v136
	v_ashrrev_i32_e32 v133, 31, v132
	v_lshlrev_b64 v[132:133], 13, v[132:133]
	v_lshl_add_u64 v[140:141], v[138:139], 0, v[132:133]
	v_max_f32_e32 v132, 0, v44
	v_mul_f32_e32 v134, v132, v132
	v_max_f32_e32 v133, 0, v45
	v_max_f32_e32 v132, 0, v37
	v_mul_f32_e32 v135, v133, v133
	v_mul_f32_e32 v132, v132, v132
	v_max_f32_e32 v133, 0, v38
	v_mul_f32_e32 v17, v17, v17
	v_max_f32_e32 v137, 0, v46
	v_mul_f32_e32 v133, v133, v133
	v_max_f32_e32 v142, 0, v39
	v_max_f32_e32 v143, 0, v47
	v_cvt_pk_bf16_f32 v132, v17, v132
	v_mul_f32_e32 v137, v137, v137
	v_mul_f32_e32 v142, v142, v142
	v_mul_f32_e32 v143, v143, v143
	v_cvt_pk_bf16_f32 v133, v133, v142
	v_cvt_pk_bf16_f32 v134, v134, v135
	v_cvt_pk_bf16_f32 v135, v137, v143
	global_store_dwordx4 v[140:141], v[132:135], off
	s_nop 1
	v_max_f32_e32 v17, 0, v40
	v_max_f32_e32 v132, 0, v48
	v_mul_f32_e32 v134, v132, v132
	v_max_f32_e32 v133, 0, v49
	v_max_f32_e32 v132, 0, v41
	v_mul_f32_e32 v135, v133, v133
	v_mul_f32_e32 v132, v132, v132
	v_max_f32_e32 v133, 0, v42
	v_mul_f32_e32 v17, v17, v17
	v_max_f32_e32 v137, 0, v50
	v_mul_f32_e32 v133, v133, v133
	v_max_f32_e32 v142, 0, v43
	v_max_f32_e32 v143, 0, v51
	v_cvt_pk_bf16_f32 v132, v17, v132
	v_mul_f32_e32 v137, v137, v137
	v_mul_f32_e32 v142, v142, v142
	v_mul_f32_e32 v143, v143, v143
	v_cvt_pk_bf16_f32 v133, v133, v142
	v_cvt_pk_bf16_f32 v134, v134, v135
	v_cvt_pk_bf16_f32 v135, v137, v143
	global_store_dwordx4 v[140:141], v[132:135], off offset:256
	s_nop 1
	v_max_f32_e32 v17, 0, v80
	v_or_b32_e32 v132, 48, v136
	v_ashrrev_i32_e32 v133, 31, v132
	v_lshlrev_b64 v[132:133], 13, v[132:133]
	v_lshl_add_u64 v[136:137], v[138:139], 0, v[132:133]
	v_max_f32_e32 v132, 0, v88
	v_max_f32_e32 v133, 0, v89
	v_mul_f32_e32 v134, v132, v132
	v_mul_f32_e32 v135, v133, v133
	v_max_f32_e32 v132, 0, v81
	v_max_f32_e32 v133, 0, v82
	v_mul_f32_e32 v132, v132, v132
	v_mul_f32_e32 v133, v133, v133
	v_max_f32_e32 v139, 0, v83
	v_mul_f32_e32 v17, v17, v17
	v_max_f32_e32 v138, 0, v90
	v_max_f32_e32 v140, 0, v91
	v_mul_f32_e32 v139, v139, v139
	v_cvt_pk_bf16_f32 v132, v17, v132
	v_cvt_pk_bf16_f32 v133, v133, v139
	v_mul_f32_e32 v138, v138, v138
	v_mul_f32_e32 v140, v140, v140
	v_cvt_pk_bf16_f32 v134, v134, v135
	v_cvt_pk_bf16_f32 v135, v138, v140
	global_store_dwordx4 v[136:137], v[132:135], off
	s_nop 1
	v_max_f32_e32 v132, 0, v64
	v_max_f32_e32 v133, 0, v65
	v_mul_f32_e32 v134, v132, v132
	v_mul_f32_e32 v135, v133, v133
	v_max_f32_e32 v132, 0, v61
	v_max_f32_e32 v133, 0, v62
	v_max_f32_e32 v17, 0, v60
	v_mul_f32_e32 v132, v132, v132
	v_mul_f32_e32 v133, v133, v133
	v_max_f32_e32 v139, 0, v63
	v_mul_f32_e32 v17, v17, v17
	v_max_f32_e32 v138, 0, v66
	v_max_f32_e32 v140, 0, v67
	v_mul_f32_e32 v139, v139, v139
	v_cvt_pk_bf16_f32 v132, v17, v132
	v_cvt_pk_bf16_f32 v133, v133, v139
	v_mul_f32_e32 v138, v138, v138
	v_mul_f32_e32 v140, v140, v140
	v_cvt_pk_bf16_f32 v134, v134, v135
	v_cvt_pk_bf16_f32 v135, v138, v140
	global_store_dwordx4 v[136:137], v[132:135], off offset:256
	s_nop 1
	s_mov_b64 s[0:1], 0x100000
	v_max_f32_e32 v132, 0, v72
	v_max_f32_e32 v133, 0, v73
	v_mul_f32_e32 v134, v132, v132
	v_mul_f32_e32 v135, v133, v133
	v_max_f32_e32 v132, 0, v69
	v_max_f32_e32 v133, 0, v70
	v_max_f32_e32 v138, 0, v74
	v_lshl_add_u64 v[136:137], v[18:19], 0, s[0:1]
	v_max_f32_e32 v17, 0, v68
	v_mul_f32_e32 v132, v132, v132
	v_mul_f32_e32 v133, v133, v133
	v_mul_f32_e32 v138, v138, v138
	v_max_f32_e32 v139, 0, v71
	v_max_f32_e32 v140, 0, v75
	s_mov_b32 s0, 0x100000
	v_mul_f32_e32 v17, v17, v17
	v_mul_f32_e32 v139, v139, v139
	v_mul_f32_e32 v140, v140, v140
	v_cvt_pk_bf16_f32 v132, v17, v132
	v_cvt_pk_bf16_f32 v133, v133, v139
	v_cvt_pk_bf16_f32 v134, v134, v135
	v_cvt_pk_bf16_f32 v135, v138, v140
	v_add_co_u32_e32 v138, vcc, s0, v18
	s_nop 0
	s_nop 0
	v_addc_co_u32_e32 v139, vcc, 0, v19, vcc
	global_store_dwordx4 v[138:139], v[132:135], off
	s_nop 0
	v_max_f32_e32 v17, 0, v52
	s_nop 0
	s_nop 0
	v_max_f32_e32 v132, 0, v56
	v_max_f32_e32 v133, 0, v57
	v_mul_f32_e32 v134, v132, v132
	v_mul_f32_e32 v135, v133, v133
	v_max_f32_e32 v132, 0, v53
	v_max_f32_e32 v133, 0, v54
	v_mul_f32_e32 v132, v132, v132
	v_mul_f32_e32 v133, v133, v133
	v_max_f32_e32 v139, 0, v55
	v_mul_f32_e32 v17, v17, v17
	v_max_f32_e32 v138, 0, v58
	v_max_f32_e32 v140, 0, v59
	v_mul_f32_e32 v139, v139, v139
	v_cvt_pk_bf16_f32 v132, v17, v132
	v_cvt_pk_bf16_f32 v133, v133, v139
	v_mul_f32_e32 v138, v138, v138
	v_mul_f32_e32 v140, v140, v140
	v_cvt_pk_bf16_f32 v134, v134, v135
	v_cvt_pk_bf16_f32 v135, v138, v140
	global_store_dwordx4 v[136:137], v[132:135], off offset:256
	s_nop 1
	s_mov_b64 s[0:1], 0x120000
	v_max_f32_e32 v132, 0, v96
	v_max_f32_e32 v133, 0, v97
	v_mul_f32_e32 v134, v132, v132
	v_mul_f32_e32 v135, v133, v133
	v_max_f32_e32 v132, 0, v93
	v_max_f32_e32 v133, 0, v94
	v_max_f32_e32 v138, 0, v98
	v_lshl_add_u64 v[136:137], v[18:19], 0, s[0:1]
	v_max_f32_e32 v17, 0, v92
	v_mul_f32_e32 v132, v132, v132
	v_mul_f32_e32 v133, v133, v133
	v_mul_f32_e32 v138, v138, v138
	v_max_f32_e32 v139, 0, v95
	v_max_f32_e32 v140, 0, v99
	s_mov_b32 s0, 0x120000
	v_mul_f32_e32 v17, v17, v17
	v_mul_f32_e32 v139, v139, v139
	v_mul_f32_e32 v140, v140, v140
	v_cvt_pk_bf16_f32 v132, v17, v132
	v_cvt_pk_bf16_f32 v133, v133, v139
	v_cvt_pk_bf16_f32 v134, v134, v135
	v_cvt_pk_bf16_f32 v135, v138, v140
	v_add_co_u32_e32 v138, vcc, s0, v18
	s_nop 0
	s_nop 0
	v_addc_co_u32_e32 v139, vcc, 0, v19, vcc
	global_store_dwordx4 v[138:139], v[132:135], off
	s_nop 0
	v_max_f32_e32 v17, 0, v76
	s_nop 0
	s_nop 0
	v_max_f32_e32 v132, 0, v84
	v_max_f32_e32 v133, 0, v85
	v_mul_f32_e32 v134, v132, v132
	v_mul_f32_e32 v135, v133, v133
	v_max_f32_e32 v132, 0, v77
	v_max_f32_e32 v133, 0, v78
	v_mul_f32_e32 v132, v132, v132
	v_mul_f32_e32 v133, v133, v133
	v_max_f32_e32 v139, 0, v79
	v_mul_f32_e32 v17, v17, v17
	v_max_f32_e32 v138, 0, v86
	v_max_f32_e32 v140, 0, v87
	v_mul_f32_e32 v139, v139, v139
	v_cvt_pk_bf16_f32 v132, v17, v132
	v_cvt_pk_bf16_f32 v133, v133, v139
	v_mul_f32_e32 v138, v138, v138
	v_mul_f32_e32 v140, v140, v140
	v_cvt_pk_bf16_f32 v134, v134, v135
	v_cvt_pk_bf16_f32 v135, v138, v140
	global_store_dwordx4 v[136:137], v[132:135], off offset:256
	s_nop 1
	s_mov_b64 s[0:1], 0x140000
	v_max_f32_e32 v132, 0, v112
	v_max_f32_e32 v133, 0, v113
	v_mul_f32_e32 v134, v132, v132
	v_mul_f32_e32 v135, v133, v133
	v_max_f32_e32 v132, 0, v109
	v_max_f32_e32 v133, 0, v110
	v_max_f32_e32 v138, 0, v114
	v_lshl_add_u64 v[136:137], v[18:19], 0, s[0:1]
	v_max_f32_e32 v17, 0, v108
	v_mul_f32_e32 v132, v132, v132
	v_mul_f32_e32 v133, v133, v133
	v_mul_f32_e32 v138, v138, v138
	v_max_f32_e32 v139, 0, v111
	v_max_f32_e32 v140, 0, v115
	s_mov_b32 s0, 0x140000
	v_mul_f32_e32 v17, v17, v17
	v_mul_f32_e32 v139, v139, v139
	v_mul_f32_e32 v140, v140, v140
	v_cvt_pk_bf16_f32 v132, v17, v132
	v_cvt_pk_bf16_f32 v133, v133, v139
	v_cvt_pk_bf16_f32 v134, v134, v135
	v_cvt_pk_bf16_f32 v135, v138, v140
	v_add_co_u32_e32 v138, vcc, s0, v18
	s_nop 0
	s_nop 0
	v_addc_co_u32_e32 v139, vcc, 0, v19, vcc
	global_store_dwordx4 v[138:139], v[132:135], off
	s_nop 1
	v_max_f32_e32 v17, 0, v100
	v_max_f32_e32 v132, 0, v104
	v_mul_f32_e32 v134, v132, v132
	v_max_f32_e32 v133, 0, v105
	v_max_f32_e32 v132, 0, v101
	v_mul_f32_e32 v135, v133, v133
	v_mul_f32_e32 v132, v132, v132
	v_max_f32_e32 v133, 0, v102
	v_mul_f32_e32 v17, v17, v17
	v_max_f32_e32 v138, 0, v106
	v_mul_f32_e32 v133, v133, v133
	v_max_f32_e32 v139, 0, v103
	v_max_f32_e32 v140, 0, v107
	v_cvt_pk_bf16_f32 v132, v17, v132
	v_mul_f32_e32 v138, v138, v138
	v_mul_f32_e32 v139, v139, v139
	v_mul_f32_e32 v140, v140, v140
	v_cvt_pk_bf16_f32 v133, v133, v139
	v_cvt_pk_bf16_f32 v134, v134, v135
	v_cvt_pk_bf16_f32 v135, v138, v140
	global_store_dwordx4 v[136:137], v[132:135], off offset:256
	s_mov_b64 s[0:1], 0x160000
	v_lshl_add_u64 v[136:137], v[18:19], 0, s[0:1]
	v_max_f32_e32 v132, 0, v128
	v_mul_f32_e32 v134, v132, v132
	v_max_f32_e32 v133, 0, v129
	v_max_f32_e32 v132, 0, v125
	v_mul_f32_e32 v135, v133, v133
	s_mov_b32 s0, 0x160000
	v_max_f32_e32 v17, 0, v124
	v_mul_f32_e32 v132, v132, v132
	v_max_f32_e32 v133, 0, v126
	s_nop 0
	s_nop 0
	v_add_co_u32_e32 v18, vcc, s0, v18
	v_mul_f32_e32 v17, v17, v17
	v_max_f32_e32 v138, 0, v130
	v_mul_f32_e32 v133, v133, v133
	v_max_f32_e32 v139, 0, v127
	v_max_f32_e32 v140, 0, v131
	v_cvt_pk_bf16_f32 v132, v17, v132
	v_addc_co_u32_e32 v19, vcc, 0, v19, vcc
	v_mul_f32_e32 v138, v138, v138
	v_mul_f32_e32 v139, v139, v139
	v_mul_f32_e32 v140, v140, v140
	v_cvt_pk_bf16_f32 v133, v133, v139
	v_cvt_pk_bf16_f32 v134, v134, v135
	v_cvt_pk_bf16_f32 v135, v138, v140
	global_store_dwordx4 v[18:19], v[132:135], off
	s_nop 1
	v_max_f32_e32 v132, 0, v121
	v_mul_f32_e32 v134, v132, v132
	v_max_f32_e32 v132, 0, v118
	v_max_f32_e32 v133, 0, v122
	v_mul_f32_e32 v135, v132, v132
	v_mul_f32_e32 v138, v133, v133
	v_max_f32_e32 v17, 0, v116
	v_max_f32_e32 v18, 0, v120
	v_max_f32_e32 v19, 0, v117
	v_max_f32_e32 v132, 0, v119
	v_max_f32_e32 v133, 0, v123
	v_mul_f32_e32 v17, v17, v17
	v_mul_f32_e32 v18, v18, v18
	v_mul_f32_e32 v19, v19, v19
	v_mul_f32_e32 v139, v132, v132
	v_mul_f32_e32 v140, v133, v133
	v_cvt_pk_bf16_f32 v132, v17, v19
	v_cvt_pk_bf16_f32 v133, v135, v139
	v_cvt_pk_bf16_f32 v134, v18, v134
	v_cvt_pk_bf16_f32 v135, v138, v140
	global_store_dwordx4 v[136:137], v[132:135], off offset:256
